# top-k mask: bit-sliced radix select (per-lane 32x32 bit transpose, popcount passes) replaces the per-key compare/add counting
# speedup vs baseline: 1.0236x; 1.0045x over previous
.LBB0_592:
	s_lshl_b64 s[8:9], s[8:9], 13
	s_add_u32 s8, s18, s8
	s_addc_u32 s9, s19, s9
	global_load_dword v69, v32, s[8:9]
	global_load_dword v68, v32, s[8:9] offset:256
	global_load_dword v67, v32, s[8:9] offset:512
	global_load_dword v65, v32, s[8:9] offset:768
	global_load_dword v64, v32, s[8:9] offset:1024
	global_load_dword v3, v5, s[8:9]
	global_load_dword v38, v6, s[8:9]
	global_load_dword v39, v7, s[8:9]
	global_load_dword v40, v8, s[8:9]
	global_load_dword v41, v9, s[8:9]
	global_load_dword v42, v10, s[8:9]
	global_load_dword v43, v11, s[8:9]
	global_load_dword v44, v12, s[8:9]
	global_load_dword v45, v13, s[8:9]
	global_load_dword v46, v14, s[8:9]
	global_load_dword v47, v15, s[8:9]
	global_load_dword v48, v16, s[8:9]
	global_load_dword v49, v17, s[8:9]
	global_load_dword v50, v18, s[8:9]
	global_load_dword v51, v19, s[8:9]
	global_load_dword v52, v20, s[8:9]
	global_load_dword v53, v21, s[8:9]
	global_load_dword v54, v22, s[8:9]
	global_load_dword v61, v23, s[8:9]
	global_load_dword v62, v24, s[8:9]
	global_load_dword v63, v25, s[8:9]
	global_load_dword v76, v26, s[8:9]
	global_load_dword v77, v27, s[8:9]
	global_load_dword v78, v28, s[8:9]
	global_load_dword v79, v29, s[8:9]
	global_load_dword v80, v30, s[8:9]
	global_load_dword v81, v31, s[8:9]
	s_mov_b32 s15, 31
	s_mov_b32 s2, 0
	s_mov_b64 s[42:43], 0
	s_mov_b32 s47, 0
	s_waitcnt vmcnt(31)
	v_ashrrev_i32_e32 v2, 31, v69
	s_waitcnt vmcnt(30)
	v_ashrrev_i32_e32 v33, 31, v68
	v_or_b32_e32 v72, 0x80000000, v33
	v_bitop3_b32 v36, v33, v68, s33 bitop3:0x36
	s_waitcnt vmcnt(29)
	v_ashrrev_i32_e32 v33, 31, v67
	s_waitcnt vmcnt(26)
	v_ashrrev_i32_e32 v37, 31, v3
	v_bitop3_b32 v3, v37, v3, s33 bitop3:0x36
	v_cndmask_b32_e64 v37, v3, 0, s[24:25]
	s_waitcnt vmcnt(25)
	v_ashrrev_i32_e32 v3, 31, v38
	v_bitop3_b32 v3, v3, v38, s33 bitop3:0x36
	v_cndmask_b32_e64 v38, v3, 0, s[26:27]
	s_waitcnt vmcnt(24)
	v_ashrrev_i32_e32 v3, 31, v39
	v_bitop3_b32 v3, v3, v39, s33 bitop3:0x36
	v_cndmask_b32_e64 v39, v3, 0, s[28:29]
	s_waitcnt vmcnt(23)
	v_ashrrev_i32_e32 v3, 31, v40
	v_bitop3_b32 v3, v3, v40, s33 bitop3:0x36
	s_waitcnt vmcnt(22)
	v_ashrrev_i32_e32 v40, 31, v41
	v_bitop3_b32 v40, v40, v41, s33 bitop3:0x36
	s_waitcnt vmcnt(21)
	v_ashrrev_i32_e32 v41, 31, v42
	v_bitop3_b32 v41, v41, v42, s33 bitop3:0x36
	s_waitcnt vmcnt(20)
	v_ashrrev_i32_e32 v42, 31, v43
	v_bitop3_b32 v42, v42, v43, s33 bitop3:0x36
	s_waitcnt vmcnt(19)
	v_ashrrev_i32_e32 v43, 31, v44
	v_bitop3_b32 v43, v43, v44, s33 bitop3:0x36
	s_waitcnt vmcnt(18)
	v_ashrrev_i32_e32 v44, 31, v45
	v_bitop3_b32 v44, v44, v45, s33 bitop3:0x36
	s_waitcnt vmcnt(17)
	v_ashrrev_i32_e32 v45, 31, v46
	v_bitop3_b32 v45, v45, v46, s33 bitop3:0x36
	s_waitcnt vmcnt(16)
	v_ashrrev_i32_e32 v46, 31, v47
	v_bitop3_b32 v46, v46, v47, s33 bitop3:0x36
	s_waitcnt vmcnt(15)
	v_ashrrev_i32_e32 v47, 31, v48
	v_bitop3_b32 v66, v47, v48, s33 bitop3:0x36
	s_waitcnt vmcnt(14)
	v_ashrrev_i32_e32 v47, 31, v49
	v_bitop3_b32 v47, v47, v49, s33 bitop3:0x36
	v_cndmask_b32_e64 v60, v47, 0, s[68:69]
	s_waitcnt vmcnt(13)
	v_ashrrev_i32_e32 v47, 31, v50
	v_bitop3_b32 v47, v47, v50, s33 bitop3:0x36
	v_cndmask_b32_e64 v59, v47, 0, s[70:71]
	s_waitcnt vmcnt(12)
	v_ashrrev_i32_e32 v47, 31, v51
	v_bitop3_b32 v47, v47, v51, s33 bitop3:0x36
	v_cndmask_b32_e64 v58, v47, 0, s[72:73]
	s_waitcnt vmcnt(11)
	v_ashrrev_i32_e32 v47, 31, v52
	v_bitop3_b32 v47, v47, v52, s33 bitop3:0x36
	v_cndmask_b32_e64 v57, v47, 0, s[74:75]
	s_waitcnt vmcnt(10)
	v_ashrrev_i32_e32 v47, 31, v53
	v_bitop3_b32 v47, v47, v53, s33 bitop3:0x36
	v_cndmask_b32_e64 v56, v47, 0, s[76:77]
	s_waitcnt vmcnt(9)
	v_ashrrev_i32_e32 v47, 31, v54
	v_bitop3_b32 v47, v47, v54, s33 bitop3:0x36
	v_cndmask_b32_e64 v55, v47, 0, s[78:79]
	s_waitcnt vmcnt(8)
	v_ashrrev_i32_e32 v47, 31, v61
	v_bitop3_b32 v47, v47, v61, s33 bitop3:0x36
	v_cndmask_b32_e64 v54, v47, 0, s[80:81]
	s_waitcnt vmcnt(7)
	v_ashrrev_i32_e32 v47, 31, v62
	v_bitop3_b32 v70, v47, v62, s33 bitop3:0x36
	s_waitcnt vmcnt(6)
	v_ashrrev_i32_e32 v47, 31, v63
	v_bitop3_b32 v47, v47, v63, s33 bitop3:0x36
	v_cndmask_b32_e64 v53, v47, 0, s[86:87]
	s_waitcnt vmcnt(5)
	v_ashrrev_i32_e32 v47, 31, v76
	v_bitop3_b32 v47, v47, v76, s33 bitop3:0x36
	v_cndmask_b32_e64 v52, v47, 0, s[88:89]
	s_waitcnt vmcnt(4)
	v_ashrrev_i32_e32 v47, 31, v77
	v_bitop3_b32 v47, v47, v77, s33 bitop3:0x36
	v_cndmask_b32_e64 v51, v47, 0, s[90:91]
	s_waitcnt vmcnt(3)
	v_ashrrev_i32_e32 v47, 31, v78
	v_bitop3_b32 v47, v47, v78, s33 bitop3:0x36
	v_cndmask_b32_e64 v50, v47, 0, s[92:93]
	s_waitcnt vmcnt(2)
	v_ashrrev_i32_e32 v47, 31, v79
	v_bitop3_b32 v47, v47, v79, s33 bitop3:0x36
	v_cndmask_b32_e64 v49, v47, 0, s[94:95]
	s_waitcnt vmcnt(1)
	v_ashrrev_i32_e32 v47, 31, v80
	v_bitop3_b32 v47, v47, v80, s33 bitop3:0x36
	v_or_b32_e32 v73, 0x80000000, v33
	v_bitop3_b32 v35, v33, v67, s33 bitop3:0x36
	v_ashrrev_i32_e32 v33, 31, v65
	v_cndmask_b32_e64 v48, v47, 0, s[96:97]
	s_waitcnt vmcnt(0)
	v_ashrrev_i32_e32 v47, 31, v81
	v_or_b32_e32 v74, 0x80000000, v33
	v_bitop3_b32 v34, v33, v65, s33 bitop3:0x36
	v_ashrrev_i32_e32 v33, 31, v64
	v_bitop3_b32 v47, v47, v81, s33 bitop3:0x36
	v_or_b32_e32 v71, 0x80000000, v2
	v_bitop3_b32 v2, v2, v69, s33 bitop3:0x36
	v_or_b32_e32 v75, 0x80000000, v33
	v_bitop3_b32 v33, v33, v64, s33 bitop3:0x36
	v_cndmask_b32_e64 v40, v40, 0, s[50:51]
	v_cndmask_b32_e64 v41, v41, 0, s[52:53]
	v_cndmask_b32_e64 v42, v42, 0, s[54:55]
	v_cndmask_b32_e64 v43, v43, 0, s[56:57]
	v_cndmask_b32_e64 v44, v44, 0, s[58:59]
	v_cndmask_b32_e64 v45, v45, 0, s[60:61]
	v_cndmask_b32_e64 v46, v46, 0, s[62:63]
	v_cndmask_b32_e64 v47, 0, v47, s[6:7]
	v_cndmask_b32_e64 v63, v3, 0, s[30:31]
	v_cndmask_b32_e64 v62, v66, 0, s[64:65]
	v_cndmask_b32_e64 v61, v70, 0, s[82:83]
	s_mov_b32 s9, 0x05040100
	s_mov_b32 s10, 0x07060302
	s_mov_b32 s11, 0x06020400
	s_mov_b32 s12, 0x07030501
	s_mov_b32 s13, 0x0f0f0f0f
	s_mov_b32 s41, 0x33333333
	s_mov_b32 s42, 0x55555555
	v_perm_b32 v212, v62, v2, s9
	v_perm_b32 v228, v62, v2, s10
	v_perm_b32 v213, v60, v36, s9
	v_perm_b32 v229, v60, v36, s10
	v_perm_b32 v214, v59, v35, s9
	v_perm_b32 v230, v59, v35, s10
	v_perm_b32 v215, v58, v34, s9
	v_perm_b32 v231, v58, v34, s10
	v_perm_b32 v216, v57, v33, s9
	v_perm_b32 v232, v57, v33, s10
	v_perm_b32 v217, v56, v37, s9
	v_perm_b32 v233, v56, v37, s10
	v_perm_b32 v218, v55, v38, s9
	v_perm_b32 v234, v55, v38, s10
	v_perm_b32 v219, v54, v39, s9
	v_perm_b32 v235, v54, v39, s10
	v_perm_b32 v220, v61, v63, s9
	v_perm_b32 v236, v61, v63, s10
	v_perm_b32 v221, v53, v40, s9
	v_perm_b32 v237, v53, v40, s10
	v_perm_b32 v222, v52, v41, s9
	v_perm_b32 v238, v52, v41, s10
	v_perm_b32 v223, v51, v42, s9
	v_perm_b32 v239, v51, v42, s10
	v_perm_b32 v224, v50, v43, s9
	v_perm_b32 v240, v50, v43, s10
	v_perm_b32 v225, v49, v44, s9
	v_perm_b32 v241, v49, v44, s10
	v_perm_b32 v226, v48, v45, s9
	v_perm_b32 v242, v48, v45, s10
	v_perm_b32 v227, v47, v46, s9
	v_perm_b32 v243, v47, v46, s10
	v_perm_b32 v244, v220, v212, s11
	v_perm_b32 v220, v220, v212, s12
	v_perm_b32 v212, v221, v213, s11
	v_perm_b32 v221, v221, v213, s12
	v_perm_b32 v213, v222, v214, s11
	v_perm_b32 v222, v222, v214, s12
	v_perm_b32 v214, v223, v215, s11
	v_perm_b32 v223, v223, v215, s12
	v_perm_b32 v215, v224, v216, s11
	v_perm_b32 v224, v224, v216, s12
	v_perm_b32 v216, v225, v217, s11
	v_perm_b32 v225, v225, v217, s12
	v_perm_b32 v217, v226, v218, s11
	v_perm_b32 v226, v226, v218, s12
	v_perm_b32 v218, v227, v219, s11
	v_perm_b32 v227, v227, v219, s12
	v_perm_b32 v219, v236, v228, s11
	v_perm_b32 v236, v236, v228, s12
	v_perm_b32 v228, v237, v229, s11
	v_perm_b32 v237, v237, v229, s12
	v_perm_b32 v229, v238, v230, s11
	v_perm_b32 v238, v238, v230, s12
	v_perm_b32 v230, v239, v231, s11
	v_perm_b32 v239, v239, v231, s12
	v_perm_b32 v231, v240, v232, s11
	v_perm_b32 v240, v240, v232, s12
	v_perm_b32 v232, v241, v233, s11
	v_perm_b32 v241, v241, v233, s12
	v_perm_b32 v233, v242, v234, s11
	v_perm_b32 v242, v242, v234, s12
	v_perm_b32 v234, v243, v235, s11
	v_perm_b32 v243, v243, v235, s12
	v_lshlrev_b32_e32 v245, 4, v215
	v_lshrrev_b32_e32 v246, 4, v244
	v_bfi_b32 v235, s13, v244, v245
	v_bfi_b32 v215, s13, v246, v215
	v_lshlrev_b32_e32 v245, 4, v216
	v_lshrrev_b32_e32 v246, 4, v212
	v_bfi_b32 v244, s13, v212, v245
	v_bfi_b32 v216, s13, v246, v216
	v_lshlrev_b32_e32 v245, 4, v217
	v_lshrrev_b32_e32 v246, 4, v213
	v_bfi_b32 v212, s13, v213, v245
	v_bfi_b32 v217, s13, v246, v217
	v_lshlrev_b32_e32 v245, 4, v218
	v_lshrrev_b32_e32 v246, 4, v214
	v_bfi_b32 v213, s13, v214, v245
	v_bfi_b32 v218, s13, v246, v218
	v_lshlrev_b32_e32 v245, 4, v224
	v_lshrrev_b32_e32 v246, 4, v220
	v_bfi_b32 v214, s13, v220, v245
	v_bfi_b32 v224, s13, v246, v224
	v_lshlrev_b32_e32 v245, 4, v225
	v_lshrrev_b32_e32 v246, 4, v221
	v_bfi_b32 v220, s13, v221, v245
	v_bfi_b32 v225, s13, v246, v225
	v_lshlrev_b32_e32 v245, 4, v226
	v_lshrrev_b32_e32 v246, 4, v222
	v_bfi_b32 v221, s13, v222, v245
	v_bfi_b32 v226, s13, v246, v226
	v_lshlrev_b32_e32 v245, 4, v227
	v_lshrrev_b32_e32 v246, 4, v223
	v_bfi_b32 v222, s13, v223, v245
	v_bfi_b32 v227, s13, v246, v227
	v_lshlrev_b32_e32 v245, 4, v231
	v_lshrrev_b32_e32 v246, 4, v219
	v_bfi_b32 v223, s13, v219, v245
	v_bfi_b32 v231, s13, v246, v231
	v_lshlrev_b32_e32 v245, 4, v232
	v_lshrrev_b32_e32 v246, 4, v228
	v_bfi_b32 v219, s13, v228, v245
	v_bfi_b32 v232, s13, v246, v232
	v_lshlrev_b32_e32 v245, 4, v233
	v_lshrrev_b32_e32 v246, 4, v229
	v_bfi_b32 v228, s13, v229, v245
	v_bfi_b32 v233, s13, v246, v233
	v_lshlrev_b32_e32 v245, 4, v234
	v_lshrrev_b32_e32 v246, 4, v230
	v_bfi_b32 v229, s13, v230, v245
	v_bfi_b32 v234, s13, v246, v234
	v_lshlrev_b32_e32 v245, 4, v240
	v_lshrrev_b32_e32 v246, 4, v236
	v_bfi_b32 v230, s13, v236, v245
	v_bfi_b32 v240, s13, v246, v240
	v_lshlrev_b32_e32 v245, 4, v241
	v_lshrrev_b32_e32 v246, 4, v237
	v_bfi_b32 v236, s13, v237, v245
	v_bfi_b32 v241, s13, v246, v241
	v_lshlrev_b32_e32 v245, 4, v242
	v_lshrrev_b32_e32 v246, 4, v238
	v_bfi_b32 v237, s13, v238, v245
	v_bfi_b32 v242, s13, v246, v242
	v_lshlrev_b32_e32 v245, 4, v243
	v_lshrrev_b32_e32 v246, 4, v239
	v_bfi_b32 v238, s13, v239, v245
	v_bfi_b32 v243, s13, v246, v243
	v_lshlrev_b32_e32 v245, 2, v212
	v_lshrrev_b32_e32 v246, 2, v235
	v_bfi_b32 v239, s41, v235, v245
	v_bfi_b32 v212, s41, v246, v212
	v_lshlrev_b32_e32 v245, 2, v213
	v_lshrrev_b32_e32 v246, 2, v244
	v_bfi_b32 v235, s41, v244, v245
	v_bfi_b32 v213, s41, v246, v213
	v_lshlrev_b32_e32 v245, 2, v217
	v_lshrrev_b32_e32 v246, 2, v215
	v_bfi_b32 v244, s41, v215, v245
	v_bfi_b32 v217, s41, v246, v217
	v_lshlrev_b32_e32 v245, 2, v218
	v_lshrrev_b32_e32 v246, 2, v216
	v_bfi_b32 v215, s41, v216, v245
	v_bfi_b32 v218, s41, v246, v218
	v_lshlrev_b32_e32 v245, 2, v221
	v_lshrrev_b32_e32 v246, 2, v214
	v_bfi_b32 v216, s41, v214, v245
	v_bfi_b32 v221, s41, v246, v221
	v_lshlrev_b32_e32 v245, 2, v222
	v_lshrrev_b32_e32 v246, 2, v220
	v_bfi_b32 v214, s41, v220, v245
	v_bfi_b32 v222, s41, v246, v222
	v_lshlrev_b32_e32 v245, 2, v226
	v_lshrrev_b32_e32 v246, 2, v224
	v_bfi_b32 v220, s41, v224, v245
	v_bfi_b32 v226, s41, v246, v226
	v_lshlrev_b32_e32 v245, 2, v227
	v_lshrrev_b32_e32 v246, 2, v225
	v_bfi_b32 v224, s41, v225, v245
	v_bfi_b32 v227, s41, v246, v227
	v_lshlrev_b32_e32 v245, 2, v228
	v_lshrrev_b32_e32 v246, 2, v223
	v_bfi_b32 v225, s41, v223, v245
	v_bfi_b32 v228, s41, v246, v228
	v_lshlrev_b32_e32 v245, 2, v229
	v_lshrrev_b32_e32 v246, 2, v219
	v_bfi_b32 v223, s41, v219, v245
	v_bfi_b32 v229, s41, v246, v229
	v_lshlrev_b32_e32 v245, 2, v233
	v_lshrrev_b32_e32 v246, 2, v231
	v_bfi_b32 v219, s41, v231, v245
	v_bfi_b32 v233, s41, v246, v233
	v_lshlrev_b32_e32 v245, 2, v234
	v_lshrrev_b32_e32 v246, 2, v232
	v_bfi_b32 v231, s41, v232, v245
	v_bfi_b32 v234, s41, v246, v234
	v_lshlrev_b32_e32 v245, 2, v237
	v_lshrrev_b32_e32 v246, 2, v230
	v_bfi_b32 v232, s41, v230, v245
	v_bfi_b32 v237, s41, v246, v237
	v_lshlrev_b32_e32 v245, 2, v238
	v_lshrrev_b32_e32 v246, 2, v236
	v_bfi_b32 v230, s41, v236, v245
	v_bfi_b32 v238, s41, v246, v238
	v_lshlrev_b32_e32 v245, 2, v242
	v_lshrrev_b32_e32 v246, 2, v240
	v_bfi_b32 v236, s41, v240, v245
	v_bfi_b32 v242, s41, v246, v242
	v_lshlrev_b32_e32 v245, 2, v243
	v_lshrrev_b32_e32 v246, 2, v241
	v_bfi_b32 v240, s41, v241, v245
	v_bfi_b32 v243, s41, v246, v243
	v_lshlrev_b32_e32 v245, 1, v235
	v_lshrrev_b32_e32 v246, 1, v239
	v_bfi_b32 v241, s42, v239, v245
	v_bfi_b32 v235, s42, v246, v235
	v_lshlrev_b32_e32 v245, 1, v213
	v_lshrrev_b32_e32 v246, 1, v212
	v_bfi_b32 v239, s42, v212, v245
	v_bfi_b32 v213, s42, v246, v213
	v_lshlrev_b32_e32 v245, 1, v215
	v_lshrrev_b32_e32 v246, 1, v244
	v_bfi_b32 v212, s42, v244, v245
	v_bfi_b32 v215, s42, v246, v215
	v_lshlrev_b32_e32 v245, 1, v218
	v_lshrrev_b32_e32 v246, 1, v217
	v_bfi_b32 v244, s42, v217, v245
	v_bfi_b32 v218, s42, v246, v218
	v_lshlrev_b32_e32 v245, 1, v214
	v_lshrrev_b32_e32 v246, 1, v216
	v_bfi_b32 v217, s42, v216, v245
	v_bfi_b32 v214, s42, v246, v214
	v_lshlrev_b32_e32 v245, 1, v222
	v_lshrrev_b32_e32 v246, 1, v221
	v_bfi_b32 v216, s42, v221, v245
	v_bfi_b32 v222, s42, v246, v222
	v_lshlrev_b32_e32 v245, 1, v224
	v_lshrrev_b32_e32 v246, 1, v220
	v_bfi_b32 v221, s42, v220, v245
	v_bfi_b32 v224, s42, v246, v224
	v_lshlrev_b32_e32 v245, 1, v227
	v_lshrrev_b32_e32 v246, 1, v226
	v_bfi_b32 v220, s42, v226, v245
	v_bfi_b32 v227, s42, v246, v227
	v_lshlrev_b32_e32 v245, 1, v223
	v_lshrrev_b32_e32 v246, 1, v225
	v_bfi_b32 v226, s42, v225, v245
	v_bfi_b32 v223, s42, v246, v223
	v_lshlrev_b32_e32 v245, 1, v229
	v_lshrrev_b32_e32 v246, 1, v228
	v_bfi_b32 v225, s42, v228, v245
	v_bfi_b32 v229, s42, v246, v229
	v_lshlrev_b32_e32 v245, 1, v231
	v_lshrrev_b32_e32 v246, 1, v219
	v_bfi_b32 v228, s42, v219, v245
	v_bfi_b32 v231, s42, v246, v231
	v_lshlrev_b32_e32 v245, 1, v234
	v_lshrrev_b32_e32 v246, 1, v233
	v_bfi_b32 v219, s42, v233, v245
	v_bfi_b32 v234, s42, v246, v234
	v_lshlrev_b32_e32 v245, 1, v230
	v_lshrrev_b32_e32 v246, 1, v232
	v_bfi_b32 v233, s42, v232, v245
	v_bfi_b32 v230, s42, v246, v230
	v_lshlrev_b32_e32 v245, 1, v238
	v_lshrrev_b32_e32 v246, 1, v237
	v_bfi_b32 v232, s42, v237, v245
	v_bfi_b32 v238, s42, v246, v238
	v_lshlrev_b32_e32 v245, 1, v240
	v_lshrrev_b32_e32 v246, 1, v236
	v_bfi_b32 v237, s42, v236, v245
	v_bfi_b32 v240, s42, v246, v240
	v_lshlrev_b32_e32 v245, 1, v243
	v_lshrrev_b32_e32 v246, 1, v242
	v_bfi_b32 v236, s42, v242, v245
	v_bfi_b32 v243, s42, v246, v243
	v_mov_b32_e32 v247, -1
	v_mov_b32_e32 v248, 0
	s_mov_b32 s2, 0
	v_and_b32_e32 v249, v247, v243
	v_bcnt_u32_b32 v77, v249, v248
	v_xor_b32_e32 v79, v247, v249
	s_nop 0
	v_add_u32_dpp v78, v77, v77 row_shr:1 row_mask:0xf bank_mask:0xf bound_ctrl:0
	s_nop 1
	v_add_u32_dpp v78, v78, v78 row_shr:2 row_mask:0xf bank_mask:0xf
	s_nop 1
	v_add_u32_dpp v78, v78, v78 row_shr:4 row_mask:0xf bank_mask:0xf
	s_nop 1
	v_add_u32_dpp v78, v78, v78 row_shr:8 row_mask:0xf bank_mask:0xf
	s_nop 1
	v_add_u32_dpp v78, v78, v78 row_bcast:15 row_mask:0xa bank_mask:0xf
	s_nop 1
	v_add_u32_dpp v78, v78, v78 row_bcast:31 row_mask:0xc bank_mask:0xf
	s_nop 1
	v_readlane_b32 s46, v78, 63
	s_cmpk_lt_u32 s46, 0x100
	s_cselect_b64 s[98:99], -1, 0
	s_cselect_b32 s8, 0, 0x80000000
	s_or_b32 s2, s2, s8
	v_cndmask_b32_e64 v247, v249, v79, s[98:99]
	v_cndmask_b32_e64 v248, v248, v77, s[98:99]
	s_cmpk_eq_u32 s46, 0x100
	s_cbranch_scc1 .Lmy_tk_done
	v_and_b32_e32 v249, v247, v236
	v_bcnt_u32_b32 v77, v249, v248
	v_xor_b32_e32 v79, v247, v249
	s_nop 0
	v_add_u32_dpp v78, v77, v77 row_shr:1 row_mask:0xf bank_mask:0xf bound_ctrl:0
	s_nop 1
	v_add_u32_dpp v78, v78, v78 row_shr:2 row_mask:0xf bank_mask:0xf
	s_nop 1
	v_add_u32_dpp v78, v78, v78 row_shr:4 row_mask:0xf bank_mask:0xf
	s_nop 1
	v_add_u32_dpp v78, v78, v78 row_shr:8 row_mask:0xf bank_mask:0xf
	s_nop 1
	v_add_u32_dpp v78, v78, v78 row_bcast:15 row_mask:0xa bank_mask:0xf
	s_nop 1
	v_add_u32_dpp v78, v78, v78 row_bcast:31 row_mask:0xc bank_mask:0xf
	s_nop 1
	v_readlane_b32 s46, v78, 63
	s_cmpk_lt_u32 s46, 0x100
	s_cselect_b64 s[98:99], -1, 0
	s_cselect_b32 s8, 0, 0x40000000
	s_or_b32 s2, s2, s8
	v_cndmask_b32_e64 v247, v249, v79, s[98:99]
	v_cndmask_b32_e64 v248, v248, v77, s[98:99]
	s_cmpk_eq_u32 s46, 0x100
	s_cbranch_scc1 .Lmy_tk_done
	v_and_b32_e32 v249, v247, v240
	v_bcnt_u32_b32 v77, v249, v248
	v_xor_b32_e32 v79, v247, v249
	s_nop 0
	v_add_u32_dpp v78, v77, v77 row_shr:1 row_mask:0xf bank_mask:0xf bound_ctrl:0
	s_nop 1
	v_add_u32_dpp v78, v78, v78 row_shr:2 row_mask:0xf bank_mask:0xf
	s_nop 1
	v_add_u32_dpp v78, v78, v78 row_shr:4 row_mask:0xf bank_mask:0xf
	s_nop 1
	v_add_u32_dpp v78, v78, v78 row_shr:8 row_mask:0xf bank_mask:0xf
	s_nop 1
	v_add_u32_dpp v78, v78, v78 row_bcast:15 row_mask:0xa bank_mask:0xf
	s_nop 1
	v_add_u32_dpp v78, v78, v78 row_bcast:31 row_mask:0xc bank_mask:0xf
	s_nop 1
	v_readlane_b32 s46, v78, 63
	s_cmpk_lt_u32 s46, 0x100
	s_cselect_b64 s[98:99], -1, 0
	s_cselect_b32 s8, 0, 0x20000000
	s_or_b32 s2, s2, s8
	v_cndmask_b32_e64 v247, v249, v79, s[98:99]
	v_cndmask_b32_e64 v248, v248, v77, s[98:99]
	s_cmpk_eq_u32 s46, 0x100
	s_cbranch_scc1 .Lmy_tk_done
	v_and_b32_e32 v249, v247, v237
	v_bcnt_u32_b32 v77, v249, v248
	v_xor_b32_e32 v79, v247, v249
	s_nop 0
	v_add_u32_dpp v78, v77, v77 row_shr:1 row_mask:0xf bank_mask:0xf bound_ctrl:0
	s_nop 1
	v_add_u32_dpp v78, v78, v78 row_shr:2 row_mask:0xf bank_mask:0xf
	s_nop 1
	v_add_u32_dpp v78, v78, v78 row_shr:4 row_mask:0xf bank_mask:0xf
	s_nop 1
	v_add_u32_dpp v78, v78, v78 row_shr:8 row_mask:0xf bank_mask:0xf
	s_nop 1
	v_add_u32_dpp v78, v78, v78 row_bcast:15 row_mask:0xa bank_mask:0xf
	s_nop 1
	v_add_u32_dpp v78, v78, v78 row_bcast:31 row_mask:0xc bank_mask:0xf
	s_nop 1
	v_readlane_b32 s46, v78, 63
	s_cmpk_lt_u32 s46, 0x100
	s_cselect_b64 s[98:99], -1, 0
	s_cselect_b32 s8, 0, 0x10000000
	s_or_b32 s2, s2, s8
	v_cndmask_b32_e64 v247, v249, v79, s[98:99]
	v_cndmask_b32_e64 v248, v248, v77, s[98:99]
	s_cmpk_eq_u32 s46, 0x100
	s_cbranch_scc1 .Lmy_tk_done
	v_and_b32_e32 v249, v247, v238
	v_bcnt_u32_b32 v77, v249, v248
	v_xor_b32_e32 v79, v247, v249
	s_nop 0
	v_add_u32_dpp v78, v77, v77 row_shr:1 row_mask:0xf bank_mask:0xf bound_ctrl:0
	s_nop 1
	v_add_u32_dpp v78, v78, v78 row_shr:2 row_mask:0xf bank_mask:0xf
	s_nop 1
	v_add_u32_dpp v78, v78, v78 row_shr:4 row_mask:0xf bank_mask:0xf
	s_nop 1
	v_add_u32_dpp v78, v78, v78 row_shr:8 row_mask:0xf bank_mask:0xf
	s_nop 1
	v_add_u32_dpp v78, v78, v78 row_bcast:15 row_mask:0xa bank_mask:0xf
	s_nop 1
	v_add_u32_dpp v78, v78, v78 row_bcast:31 row_mask:0xc bank_mask:0xf
	s_nop 1
	v_readlane_b32 s46, v78, 63
	s_cmpk_lt_u32 s46, 0x100
	s_cselect_b64 s[98:99], -1, 0
	s_cselect_b32 s8, 0, 0x08000000
	s_or_b32 s2, s2, s8
	v_cndmask_b32_e64 v247, v249, v79, s[98:99]
	v_cndmask_b32_e64 v248, v248, v77, s[98:99]
	s_cmpk_eq_u32 s46, 0x100
	s_cbranch_scc1 .Lmy_tk_done
	v_and_b32_e32 v249, v247, v232
	v_bcnt_u32_b32 v77, v249, v248
	v_xor_b32_e32 v79, v247, v249
	s_nop 0
	v_add_u32_dpp v78, v77, v77 row_shr:1 row_mask:0xf bank_mask:0xf bound_ctrl:0
	s_nop 1
	v_add_u32_dpp v78, v78, v78 row_shr:2 row_mask:0xf bank_mask:0xf
	s_nop 1
	v_add_u32_dpp v78, v78, v78 row_shr:4 row_mask:0xf bank_mask:0xf
	s_nop 1
	v_add_u32_dpp v78, v78, v78 row_shr:8 row_mask:0xf bank_mask:0xf
	s_nop 1
	v_add_u32_dpp v78, v78, v78 row_bcast:15 row_mask:0xa bank_mask:0xf
	s_nop 1
	v_add_u32_dpp v78, v78, v78 row_bcast:31 row_mask:0xc bank_mask:0xf
	s_nop 1
	v_readlane_b32 s46, v78, 63
	s_cmpk_lt_u32 s46, 0x100
	s_cselect_b64 s[98:99], -1, 0
	s_cselect_b32 s8, 0, 0x04000000
	s_or_b32 s2, s2, s8
	v_cndmask_b32_e64 v247, v249, v79, s[98:99]
	v_cndmask_b32_e64 v248, v248, v77, s[98:99]
	s_cmpk_eq_u32 s46, 0x100
	s_cbranch_scc1 .Lmy_tk_done
	v_and_b32_e32 v249, v247, v230
	v_bcnt_u32_b32 v77, v249, v248
	v_xor_b32_e32 v79, v247, v249
	s_nop 0
	v_add_u32_dpp v78, v77, v77 row_shr:1 row_mask:0xf bank_mask:0xf bound_ctrl:0
	s_nop 1
	v_add_u32_dpp v78, v78, v78 row_shr:2 row_mask:0xf bank_mask:0xf
	s_nop 1
	v_add_u32_dpp v78, v78, v78 row_shr:4 row_mask:0xf bank_mask:0xf
	s_nop 1
	v_add_u32_dpp v78, v78, v78 row_shr:8 row_mask:0xf bank_mask:0xf
	s_nop 1
	v_add_u32_dpp v78, v78, v78 row_bcast:15 row_mask:0xa bank_mask:0xf
	s_nop 1
	v_add_u32_dpp v78, v78, v78 row_bcast:31 row_mask:0xc bank_mask:0xf
	s_nop 1
	v_readlane_b32 s46, v78, 63
	s_cmpk_lt_u32 s46, 0x100
	s_cselect_b64 s[98:99], -1, 0
	s_cselect_b32 s8, 0, 0x02000000
	s_or_b32 s2, s2, s8
	v_cndmask_b32_e64 v247, v249, v79, s[98:99]
	v_cndmask_b32_e64 v248, v248, v77, s[98:99]
	s_cmpk_eq_u32 s46, 0x100
	s_cbranch_scc1 .Lmy_tk_done
	v_and_b32_e32 v249, v247, v233
	v_bcnt_u32_b32 v77, v249, v248
	v_xor_b32_e32 v79, v247, v249
	s_nop 0
	v_add_u32_dpp v78, v77, v77 row_shr:1 row_mask:0xf bank_mask:0xf bound_ctrl:0
	s_nop 1
	v_add_u32_dpp v78, v78, v78 row_shr:2 row_mask:0xf bank_mask:0xf
	s_nop 1
	v_add_u32_dpp v78, v78, v78 row_shr:4 row_mask:0xf bank_mask:0xf
	s_nop 1
	v_add_u32_dpp v78, v78, v78 row_shr:8 row_mask:0xf bank_mask:0xf
	s_nop 1
	v_add_u32_dpp v78, v78, v78 row_bcast:15 row_mask:0xa bank_mask:0xf
	s_nop 1
	v_add_u32_dpp v78, v78, v78 row_bcast:31 row_mask:0xc bank_mask:0xf
	s_nop 1
	v_readlane_b32 s46, v78, 63
	s_cmpk_lt_u32 s46, 0x100
	s_cselect_b64 s[98:99], -1, 0
	s_cselect_b32 s8, 0, 0x01000000
	s_or_b32 s2, s2, s8
	v_cndmask_b32_e64 v247, v249, v79, s[98:99]
	v_cndmask_b32_e64 v248, v248, v77, s[98:99]
	s_cmpk_eq_u32 s46, 0x100
	s_cbranch_scc1 .Lmy_tk_done
	v_and_b32_e32 v249, v247, v234
	v_bcnt_u32_b32 v77, v249, v248
	v_xor_b32_e32 v79, v247, v249
	s_nop 0
	v_add_u32_dpp v78, v77, v77 row_shr:1 row_mask:0xf bank_mask:0xf bound_ctrl:0
	s_nop 1
	v_add_u32_dpp v78, v78, v78 row_shr:2 row_mask:0xf bank_mask:0xf
	s_nop 1
	v_add_u32_dpp v78, v78, v78 row_shr:4 row_mask:0xf bank_mask:0xf
	s_nop 1
	v_add_u32_dpp v78, v78, v78 row_shr:8 row_mask:0xf bank_mask:0xf
	s_nop 1
	v_add_u32_dpp v78, v78, v78 row_bcast:15 row_mask:0xa bank_mask:0xf
	s_nop 1
	v_add_u32_dpp v78, v78, v78 row_bcast:31 row_mask:0xc bank_mask:0xf
	s_nop 1
	v_readlane_b32 s46, v78, 63
	s_cmpk_lt_u32 s46, 0x100
	s_cselect_b64 s[98:99], -1, 0
	s_cselect_b32 s8, 0, 0x00800000
	s_or_b32 s2, s2, s8
	v_cndmask_b32_e64 v247, v249, v79, s[98:99]
	v_cndmask_b32_e64 v248, v248, v77, s[98:99]
	s_cmpk_eq_u32 s46, 0x100
	s_cbranch_scc1 .Lmy_tk_done
	v_and_b32_e32 v249, v247, v219
	v_bcnt_u32_b32 v77, v249, v248
	v_xor_b32_e32 v79, v247, v249
	s_nop 0
	v_add_u32_dpp v78, v77, v77 row_shr:1 row_mask:0xf bank_mask:0xf bound_ctrl:0
	s_nop 1
	v_add_u32_dpp v78, v78, v78 row_shr:2 row_mask:0xf bank_mask:0xf
	s_nop 1
	v_add_u32_dpp v78, v78, v78 row_shr:4 row_mask:0xf bank_mask:0xf
	s_nop 1
	v_add_u32_dpp v78, v78, v78 row_shr:8 row_mask:0xf bank_mask:0xf
	s_nop 1
	v_add_u32_dpp v78, v78, v78 row_bcast:15 row_mask:0xa bank_mask:0xf
	s_nop 1
	v_add_u32_dpp v78, v78, v78 row_bcast:31 row_mask:0xc bank_mask:0xf
	s_nop 1
	v_readlane_b32 s46, v78, 63
	s_cmpk_lt_u32 s46, 0x100
	s_cselect_b64 s[98:99], -1, 0
	s_cselect_b32 s8, 0, 0x00400000
	s_or_b32 s2, s2, s8
	v_cndmask_b32_e64 v247, v249, v79, s[98:99]
	v_cndmask_b32_e64 v248, v248, v77, s[98:99]
	s_cmpk_eq_u32 s46, 0x100
	s_cbranch_scc1 .Lmy_tk_done
	v_and_b32_e32 v249, v247, v231
	v_bcnt_u32_b32 v77, v249, v248
	v_xor_b32_e32 v79, v247, v249
	s_nop 0
	v_add_u32_dpp v78, v77, v77 row_shr:1 row_mask:0xf bank_mask:0xf bound_ctrl:0
	s_nop 1
	v_add_u32_dpp v78, v78, v78 row_shr:2 row_mask:0xf bank_mask:0xf
	s_nop 1
	v_add_u32_dpp v78, v78, v78 row_shr:4 row_mask:0xf bank_mask:0xf
	s_nop 1
	v_add_u32_dpp v78, v78, v78 row_shr:8 row_mask:0xf bank_mask:0xf
	s_nop 1
	v_add_u32_dpp v78, v78, v78 row_bcast:15 row_mask:0xa bank_mask:0xf
	s_nop 1
	v_add_u32_dpp v78, v78, v78 row_bcast:31 row_mask:0xc bank_mask:0xf
	s_nop 1
	v_readlane_b32 s46, v78, 63
	s_cmpk_lt_u32 s46, 0x100
	s_cselect_b64 s[98:99], -1, 0
	s_cselect_b32 s8, 0, 0x00200000
	s_or_b32 s2, s2, s8
	v_cndmask_b32_e64 v247, v249, v79, s[98:99]
	v_cndmask_b32_e64 v248, v248, v77, s[98:99]
	s_cmpk_eq_u32 s46, 0x100
	s_cbranch_scc1 .Lmy_tk_done
	v_and_b32_e32 v249, v247, v228
	v_bcnt_u32_b32 v77, v249, v248
	v_xor_b32_e32 v79, v247, v249
	s_nop 0
	v_add_u32_dpp v78, v77, v77 row_shr:1 row_mask:0xf bank_mask:0xf bound_ctrl:0
	s_nop 1
	v_add_u32_dpp v78, v78, v78 row_shr:2 row_mask:0xf bank_mask:0xf
	s_nop 1
	v_add_u32_dpp v78, v78, v78 row_shr:4 row_mask:0xf bank_mask:0xf
	s_nop 1
	v_add_u32_dpp v78, v78, v78 row_shr:8 row_mask:0xf bank_mask:0xf
	s_nop 1
	v_add_u32_dpp v78, v78, v78 row_bcast:15 row_mask:0xa bank_mask:0xf
	s_nop 1
	v_add_u32_dpp v78, v78, v78 row_bcast:31 row_mask:0xc bank_mask:0xf
	s_nop 1
	v_readlane_b32 s46, v78, 63
	s_cmpk_lt_u32 s46, 0x100
	s_cselect_b64 s[98:99], -1, 0
	s_cselect_b32 s8, 0, 0x00100000
	s_or_b32 s2, s2, s8
	v_cndmask_b32_e64 v247, v249, v79, s[98:99]
	v_cndmask_b32_e64 v248, v248, v77, s[98:99]
	s_cmpk_eq_u32 s46, 0x100
	s_cbranch_scc1 .Lmy_tk_done
	v_and_b32_e32 v249, v247, v229
	v_bcnt_u32_b32 v77, v249, v248
	v_xor_b32_e32 v79, v247, v249
	s_nop 0
	v_add_u32_dpp v78, v77, v77 row_shr:1 row_mask:0xf bank_mask:0xf bound_ctrl:0
	s_nop 1
	v_add_u32_dpp v78, v78, v78 row_shr:2 row_mask:0xf bank_mask:0xf
	s_nop 1
	v_add_u32_dpp v78, v78, v78 row_shr:4 row_mask:0xf bank_mask:0xf
	s_nop 1
	v_add_u32_dpp v78, v78, v78 row_shr:8 row_mask:0xf bank_mask:0xf
	s_nop 1
	v_add_u32_dpp v78, v78, v78 row_bcast:15 row_mask:0xa bank_mask:0xf
	s_nop 1
	v_add_u32_dpp v78, v78, v78 row_bcast:31 row_mask:0xc bank_mask:0xf
	s_nop 1
	v_readlane_b32 s46, v78, 63
	s_cmpk_lt_u32 s46, 0x100
	s_cselect_b64 s[98:99], -1, 0
	s_cselect_b32 s8, 0, 0x00080000
	s_or_b32 s2, s2, s8
	v_cndmask_b32_e64 v247, v249, v79, s[98:99]
	v_cndmask_b32_e64 v248, v248, v77, s[98:99]
	s_cmpk_eq_u32 s46, 0x100
	s_cbranch_scc1 .Lmy_tk_done
	v_and_b32_e32 v249, v247, v225
	v_bcnt_u32_b32 v77, v249, v248
	v_xor_b32_e32 v79, v247, v249
	s_nop 0
	v_add_u32_dpp v78, v77, v77 row_shr:1 row_mask:0xf bank_mask:0xf bound_ctrl:0
	s_nop 1
	v_add_u32_dpp v78, v78, v78 row_shr:2 row_mask:0xf bank_mask:0xf
	s_nop 1
	v_add_u32_dpp v78, v78, v78 row_shr:4 row_mask:0xf bank_mask:0xf
	s_nop 1
	v_add_u32_dpp v78, v78, v78 row_shr:8 row_mask:0xf bank_mask:0xf
	s_nop 1
	v_add_u32_dpp v78, v78, v78 row_bcast:15 row_mask:0xa bank_mask:0xf
	s_nop 1
	v_add_u32_dpp v78, v78, v78 row_bcast:31 row_mask:0xc bank_mask:0xf
	s_nop 1
	v_readlane_b32 s46, v78, 63
	s_cmpk_lt_u32 s46, 0x100
	s_cselect_b64 s[98:99], -1, 0
	s_cselect_b32 s8, 0, 0x00040000
	s_or_b32 s2, s2, s8
	v_cndmask_b32_e64 v247, v249, v79, s[98:99]
	v_cndmask_b32_e64 v248, v248, v77, s[98:99]
	s_cmpk_eq_u32 s46, 0x100
	s_cbranch_scc1 .Lmy_tk_done
	v_and_b32_e32 v249, v247, v223
	v_bcnt_u32_b32 v77, v249, v248
	v_xor_b32_e32 v79, v247, v249
	s_nop 0
	v_add_u32_dpp v78, v77, v77 row_shr:1 row_mask:0xf bank_mask:0xf bound_ctrl:0
	s_nop 1
	v_add_u32_dpp v78, v78, v78 row_shr:2 row_mask:0xf bank_mask:0xf
	s_nop 1
	v_add_u32_dpp v78, v78, v78 row_shr:4 row_mask:0xf bank_mask:0xf
	s_nop 1
	v_add_u32_dpp v78, v78, v78 row_shr:8 row_mask:0xf bank_mask:0xf
	s_nop 1
	v_add_u32_dpp v78, v78, v78 row_bcast:15 row_mask:0xa bank_mask:0xf
	s_nop 1
	v_add_u32_dpp v78, v78, v78 row_bcast:31 row_mask:0xc bank_mask:0xf
	s_nop 1
	v_readlane_b32 s46, v78, 63
	s_cmpk_lt_u32 s46, 0x100
	s_cselect_b64 s[98:99], -1, 0
	s_cselect_b32 s8, 0, 0x00020000
	s_or_b32 s2, s2, s8
	v_cndmask_b32_e64 v247, v249, v79, s[98:99]
	v_cndmask_b32_e64 v248, v248, v77, s[98:99]
	s_cmpk_eq_u32 s46, 0x100
	s_cbranch_scc1 .Lmy_tk_done
	v_and_b32_e32 v249, v247, v226
	v_bcnt_u32_b32 v77, v249, v248
	v_xor_b32_e32 v79, v247, v249
	s_nop 0
	v_add_u32_dpp v78, v77, v77 row_shr:1 row_mask:0xf bank_mask:0xf bound_ctrl:0
	s_nop 1
	v_add_u32_dpp v78, v78, v78 row_shr:2 row_mask:0xf bank_mask:0xf
	s_nop 1
	v_add_u32_dpp v78, v78, v78 row_shr:4 row_mask:0xf bank_mask:0xf
	s_nop 1
	v_add_u32_dpp v78, v78, v78 row_shr:8 row_mask:0xf bank_mask:0xf
	s_nop 1
	v_add_u32_dpp v78, v78, v78 row_bcast:15 row_mask:0xa bank_mask:0xf
	s_nop 1
	v_add_u32_dpp v78, v78, v78 row_bcast:31 row_mask:0xc bank_mask:0xf
	s_nop 1
	v_readlane_b32 s46, v78, 63
	s_cmpk_lt_u32 s46, 0x100
	s_cselect_b64 s[98:99], -1, 0
	s_cselect_b32 s8, 0, 0x00010000
	s_or_b32 s2, s2, s8
	v_cndmask_b32_e64 v247, v249, v79, s[98:99]
	v_cndmask_b32_e64 v248, v248, v77, s[98:99]
	s_cmpk_eq_u32 s46, 0x100
	s_cbranch_scc1 .Lmy_tk_done
	v_and_b32_e32 v249, v247, v227
	v_bcnt_u32_b32 v77, v249, v248
	v_xor_b32_e32 v79, v247, v249
	s_nop 0
	v_add_u32_dpp v78, v77, v77 row_shr:1 row_mask:0xf bank_mask:0xf bound_ctrl:0
	s_nop 1
	v_add_u32_dpp v78, v78, v78 row_shr:2 row_mask:0xf bank_mask:0xf
	s_nop 1
	v_add_u32_dpp v78, v78, v78 row_shr:4 row_mask:0xf bank_mask:0xf
	s_nop 1
	v_add_u32_dpp v78, v78, v78 row_shr:8 row_mask:0xf bank_mask:0xf
	s_nop 1
	v_add_u32_dpp v78, v78, v78 row_bcast:15 row_mask:0xa bank_mask:0xf
	s_nop 1
	v_add_u32_dpp v78, v78, v78 row_bcast:31 row_mask:0xc bank_mask:0xf
	s_nop 1
	v_readlane_b32 s46, v78, 63
	s_cmpk_lt_u32 s46, 0x100
	s_cselect_b64 s[98:99], -1, 0
	s_cselect_b32 s8, 0, 0x00008000
	s_or_b32 s2, s2, s8
	v_cndmask_b32_e64 v247, v249, v79, s[98:99]
	v_cndmask_b32_e64 v248, v248, v77, s[98:99]
	s_cmpk_eq_u32 s46, 0x100
	s_cbranch_scc1 .Lmy_tk_done
	v_and_b32_e32 v249, v247, v220
	v_bcnt_u32_b32 v77, v249, v248
	v_xor_b32_e32 v79, v247, v249
	s_nop 0
	v_add_u32_dpp v78, v77, v77 row_shr:1 row_mask:0xf bank_mask:0xf bound_ctrl:0
	s_nop 1
	v_add_u32_dpp v78, v78, v78 row_shr:2 row_mask:0xf bank_mask:0xf
	s_nop 1
	v_add_u32_dpp v78, v78, v78 row_shr:4 row_mask:0xf bank_mask:0xf
	s_nop 1
	v_add_u32_dpp v78, v78, v78 row_shr:8 row_mask:0xf bank_mask:0xf
	s_nop 1
	v_add_u32_dpp v78, v78, v78 row_bcast:15 row_mask:0xa bank_mask:0xf
	s_nop 1
	v_add_u32_dpp v78, v78, v78 row_bcast:31 row_mask:0xc bank_mask:0xf
	s_nop 1
	v_readlane_b32 s46, v78, 63
	s_cmpk_lt_u32 s46, 0x100
	s_cselect_b64 s[98:99], -1, 0
	s_cselect_b32 s8, 0, 0x00004000
	s_or_b32 s2, s2, s8
	v_cndmask_b32_e64 v247, v249, v79, s[98:99]
	v_cndmask_b32_e64 v248, v248, v77, s[98:99]
	s_cmpk_eq_u32 s46, 0x100
	s_cbranch_scc1 .Lmy_tk_done
	v_and_b32_e32 v249, v247, v224
	v_bcnt_u32_b32 v77, v249, v248
	v_xor_b32_e32 v79, v247, v249
	s_nop 0
	v_add_u32_dpp v78, v77, v77 row_shr:1 row_mask:0xf bank_mask:0xf bound_ctrl:0
	s_nop 1
	v_add_u32_dpp v78, v78, v78 row_shr:2 row_mask:0xf bank_mask:0xf
	s_nop 1
	v_add_u32_dpp v78, v78, v78 row_shr:4 row_mask:0xf bank_mask:0xf
	s_nop 1
	v_add_u32_dpp v78, v78, v78 row_shr:8 row_mask:0xf bank_mask:0xf
	s_nop 1
	v_add_u32_dpp v78, v78, v78 row_bcast:15 row_mask:0xa bank_mask:0xf
	s_nop 1
	v_add_u32_dpp v78, v78, v78 row_bcast:31 row_mask:0xc bank_mask:0xf
	s_nop 1
	v_readlane_b32 s46, v78, 63
	s_cmpk_lt_u32 s46, 0x100
	s_cselect_b64 s[98:99], -1, 0
	s_cselect_b32 s8, 0, 0x00002000
	s_or_b32 s2, s2, s8
	v_cndmask_b32_e64 v247, v249, v79, s[98:99]
	v_cndmask_b32_e64 v248, v248, v77, s[98:99]
	s_cmpk_eq_u32 s46, 0x100
	s_cbranch_scc1 .Lmy_tk_done
	v_and_b32_e32 v249, v247, v221
	v_bcnt_u32_b32 v77, v249, v248
	v_xor_b32_e32 v79, v247, v249
	s_nop 0
	v_add_u32_dpp v78, v77, v77 row_shr:1 row_mask:0xf bank_mask:0xf bound_ctrl:0
	s_nop 1
	v_add_u32_dpp v78, v78, v78 row_shr:2 row_mask:0xf bank_mask:0xf
	s_nop 1
	v_add_u32_dpp v78, v78, v78 row_shr:4 row_mask:0xf bank_mask:0xf
	s_nop 1
	v_add_u32_dpp v78, v78, v78 row_shr:8 row_mask:0xf bank_mask:0xf
	s_nop 1
	v_add_u32_dpp v78, v78, v78 row_bcast:15 row_mask:0xa bank_mask:0xf
	s_nop 1
	v_add_u32_dpp v78, v78, v78 row_bcast:31 row_mask:0xc bank_mask:0xf
	s_nop 1
	v_readlane_b32 s46, v78, 63
	s_cmpk_lt_u32 s46, 0x100
	s_cselect_b64 s[98:99], -1, 0
	s_cselect_b32 s8, 0, 0x00001000
	s_or_b32 s2, s2, s8
	v_cndmask_b32_e64 v247, v249, v79, s[98:99]
	v_cndmask_b32_e64 v248, v248, v77, s[98:99]
	s_cmpk_eq_u32 s46, 0x100
	s_cbranch_scc1 .Lmy_tk_done
	v_and_b32_e32 v249, v247, v222
	v_bcnt_u32_b32 v77, v249, v248
	v_xor_b32_e32 v79, v247, v249
	s_nop 0
	v_add_u32_dpp v78, v77, v77 row_shr:1 row_mask:0xf bank_mask:0xf bound_ctrl:0
	s_nop 1
	v_add_u32_dpp v78, v78, v78 row_shr:2 row_mask:0xf bank_mask:0xf
	s_nop 1
	v_add_u32_dpp v78, v78, v78 row_shr:4 row_mask:0xf bank_mask:0xf
	s_nop 1
	v_add_u32_dpp v78, v78, v78 row_shr:8 row_mask:0xf bank_mask:0xf
	s_nop 1
	v_add_u32_dpp v78, v78, v78 row_bcast:15 row_mask:0xa bank_mask:0xf
	s_nop 1
	v_add_u32_dpp v78, v78, v78 row_bcast:31 row_mask:0xc bank_mask:0xf
	s_nop 1
	v_readlane_b32 s46, v78, 63
	s_cmpk_lt_u32 s46, 0x100
	s_cselect_b64 s[98:99], -1, 0
	s_cselect_b32 s8, 0, 0x00000800
	s_or_b32 s2, s2, s8
	v_cndmask_b32_e64 v247, v249, v79, s[98:99]
	v_cndmask_b32_e64 v248, v248, v77, s[98:99]
	s_cmpk_eq_u32 s46, 0x100
	s_cbranch_scc1 .Lmy_tk_done
	v_and_b32_e32 v249, v247, v216
	v_bcnt_u32_b32 v77, v249, v248
	v_xor_b32_e32 v79, v247, v249
	s_nop 0
	v_add_u32_dpp v78, v77, v77 row_shr:1 row_mask:0xf bank_mask:0xf bound_ctrl:0
	s_nop 1
	v_add_u32_dpp v78, v78, v78 row_shr:2 row_mask:0xf bank_mask:0xf
	s_nop 1
	v_add_u32_dpp v78, v78, v78 row_shr:4 row_mask:0xf bank_mask:0xf
	s_nop 1
	v_add_u32_dpp v78, v78, v78 row_shr:8 row_mask:0xf bank_mask:0xf
	s_nop 1
	v_add_u32_dpp v78, v78, v78 row_bcast:15 row_mask:0xa bank_mask:0xf
	s_nop 1
	v_add_u32_dpp v78, v78, v78 row_bcast:31 row_mask:0xc bank_mask:0xf
	s_nop 1
	v_readlane_b32 s46, v78, 63
	s_cmpk_lt_u32 s46, 0x100
	s_cselect_b64 s[98:99], -1, 0
	s_cselect_b32 s8, 0, 0x00000400
	s_or_b32 s2, s2, s8
	v_cndmask_b32_e64 v247, v249, v79, s[98:99]
	v_cndmask_b32_e64 v248, v248, v77, s[98:99]
	s_cmpk_eq_u32 s46, 0x100
	s_cbranch_scc1 .Lmy_tk_done
	v_and_b32_e32 v249, v247, v214
	v_bcnt_u32_b32 v77, v249, v248
	v_xor_b32_e32 v79, v247, v249
	s_nop 0
	v_add_u32_dpp v78, v77, v77 row_shr:1 row_mask:0xf bank_mask:0xf bound_ctrl:0
	s_nop 1
	v_add_u32_dpp v78, v78, v78 row_shr:2 row_mask:0xf bank_mask:0xf
	s_nop 1
	v_add_u32_dpp v78, v78, v78 row_shr:4 row_mask:0xf bank_mask:0xf
	s_nop 1
	v_add_u32_dpp v78, v78, v78 row_shr:8 row_mask:0xf bank_mask:0xf
	s_nop 1
	v_add_u32_dpp v78, v78, v78 row_bcast:15 row_mask:0xa bank_mask:0xf
	s_nop 1
	v_add_u32_dpp v78, v78, v78 row_bcast:31 row_mask:0xc bank_mask:0xf
	s_nop 1
	v_readlane_b32 s46, v78, 63
	s_cmpk_lt_u32 s46, 0x100
	s_cselect_b64 s[98:99], -1, 0
	s_cselect_b32 s8, 0, 0x00000200
	s_or_b32 s2, s2, s8
	v_cndmask_b32_e64 v247, v249, v79, s[98:99]
	v_cndmask_b32_e64 v248, v248, v77, s[98:99]
	s_cmpk_eq_u32 s46, 0x100
	s_cbranch_scc1 .Lmy_tk_done
	v_and_b32_e32 v249, v247, v217
	v_bcnt_u32_b32 v77, v249, v248
	v_xor_b32_e32 v79, v247, v249
	s_nop 0
	v_add_u32_dpp v78, v77, v77 row_shr:1 row_mask:0xf bank_mask:0xf bound_ctrl:0
	s_nop 1
	v_add_u32_dpp v78, v78, v78 row_shr:2 row_mask:0xf bank_mask:0xf
	s_nop 1
	v_add_u32_dpp v78, v78, v78 row_shr:4 row_mask:0xf bank_mask:0xf
	s_nop 1
	v_add_u32_dpp v78, v78, v78 row_shr:8 row_mask:0xf bank_mask:0xf
	s_nop 1
	v_add_u32_dpp v78, v78, v78 row_bcast:15 row_mask:0xa bank_mask:0xf
	s_nop 1
	v_add_u32_dpp v78, v78, v78 row_bcast:31 row_mask:0xc bank_mask:0xf
	s_nop 1
	v_readlane_b32 s46, v78, 63
	s_cmpk_lt_u32 s46, 0x100
	s_cselect_b64 s[98:99], -1, 0
	s_cselect_b32 s8, 0, 0x00000100
	s_or_b32 s2, s2, s8
	v_cndmask_b32_e64 v247, v249, v79, s[98:99]
	v_cndmask_b32_e64 v248, v248, v77, s[98:99]
	s_cmpk_eq_u32 s46, 0x100
	s_cbranch_scc1 .Lmy_tk_done
	v_and_b32_e32 v249, v247, v218
	v_bcnt_u32_b32 v77, v249, v248
	v_xor_b32_e32 v79, v247, v249
	s_nop 0
	v_add_u32_dpp v78, v77, v77 row_shr:1 row_mask:0xf bank_mask:0xf bound_ctrl:0
	s_nop 1
	v_add_u32_dpp v78, v78, v78 row_shr:2 row_mask:0xf bank_mask:0xf
	s_nop 1
	v_add_u32_dpp v78, v78, v78 row_shr:4 row_mask:0xf bank_mask:0xf
	s_nop 1
	v_add_u32_dpp v78, v78, v78 row_shr:8 row_mask:0xf bank_mask:0xf
	s_nop 1
	v_add_u32_dpp v78, v78, v78 row_bcast:15 row_mask:0xa bank_mask:0xf
	s_nop 1
	v_add_u32_dpp v78, v78, v78 row_bcast:31 row_mask:0xc bank_mask:0xf
	s_nop 1
	v_readlane_b32 s46, v78, 63
	s_cmpk_lt_u32 s46, 0x100
	s_cselect_b64 s[98:99], -1, 0
	s_cselect_b32 s8, 0, 0x00000080
	s_or_b32 s2, s2, s8
	v_cndmask_b32_e64 v247, v249, v79, s[98:99]
	v_cndmask_b32_e64 v248, v248, v77, s[98:99]
	s_cmpk_eq_u32 s46, 0x100
	s_cbranch_scc1 .Lmy_tk_done
	v_and_b32_e32 v249, v247, v244
	v_bcnt_u32_b32 v77, v249, v248
	v_xor_b32_e32 v79, v247, v249
	s_nop 0
	v_add_u32_dpp v78, v77, v77 row_shr:1 row_mask:0xf bank_mask:0xf bound_ctrl:0
	s_nop 1
	v_add_u32_dpp v78, v78, v78 row_shr:2 row_mask:0xf bank_mask:0xf
	s_nop 1
	v_add_u32_dpp v78, v78, v78 row_shr:4 row_mask:0xf bank_mask:0xf
	s_nop 1
	v_add_u32_dpp v78, v78, v78 row_shr:8 row_mask:0xf bank_mask:0xf
	s_nop 1
	v_add_u32_dpp v78, v78, v78 row_bcast:15 row_mask:0xa bank_mask:0xf
	s_nop 1
	v_add_u32_dpp v78, v78, v78 row_bcast:31 row_mask:0xc bank_mask:0xf
	s_nop 1
	v_readlane_b32 s46, v78, 63
	s_cmpk_lt_u32 s46, 0x100
	s_cselect_b64 s[98:99], -1, 0
	s_cselect_b32 s8, 0, 0x00000040
	s_or_b32 s2, s2, s8
	v_cndmask_b32_e64 v247, v249, v79, s[98:99]
	v_cndmask_b32_e64 v248, v248, v77, s[98:99]
	s_cmpk_eq_u32 s46, 0x100
	s_cbranch_scc1 .Lmy_tk_done
	v_and_b32_e32 v249, v247, v215
	v_bcnt_u32_b32 v77, v249, v248
	v_xor_b32_e32 v79, v247, v249
	s_nop 0
	v_add_u32_dpp v78, v77, v77 row_shr:1 row_mask:0xf bank_mask:0xf bound_ctrl:0
	s_nop 1
	v_add_u32_dpp v78, v78, v78 row_shr:2 row_mask:0xf bank_mask:0xf
	s_nop 1
	v_add_u32_dpp v78, v78, v78 row_shr:4 row_mask:0xf bank_mask:0xf
	s_nop 1
	v_add_u32_dpp v78, v78, v78 row_shr:8 row_mask:0xf bank_mask:0xf
	s_nop 1
	v_add_u32_dpp v78, v78, v78 row_bcast:15 row_mask:0xa bank_mask:0xf
	s_nop 1
	v_add_u32_dpp v78, v78, v78 row_bcast:31 row_mask:0xc bank_mask:0xf
	s_nop 1
	v_readlane_b32 s46, v78, 63
	s_cmpk_lt_u32 s46, 0x100
	s_cselect_b64 s[98:99], -1, 0
	s_cselect_b32 s8, 0, 0x00000020
	s_or_b32 s2, s2, s8
	v_cndmask_b32_e64 v247, v249, v79, s[98:99]
	v_cndmask_b32_e64 v248, v248, v77, s[98:99]
	s_cmpk_eq_u32 s46, 0x100
	s_cbranch_scc1 .Lmy_tk_done
	v_and_b32_e32 v249, v247, v212
	v_bcnt_u32_b32 v77, v249, v248
	v_xor_b32_e32 v79, v247, v249
	s_nop 0
	v_add_u32_dpp v78, v77, v77 row_shr:1 row_mask:0xf bank_mask:0xf bound_ctrl:0
	s_nop 1
	v_add_u32_dpp v78, v78, v78 row_shr:2 row_mask:0xf bank_mask:0xf
	s_nop 1
	v_add_u32_dpp v78, v78, v78 row_shr:4 row_mask:0xf bank_mask:0xf
	s_nop 1
	v_add_u32_dpp v78, v78, v78 row_shr:8 row_mask:0xf bank_mask:0xf
	s_nop 1
	v_add_u32_dpp v78, v78, v78 row_bcast:15 row_mask:0xa bank_mask:0xf
	s_nop 1
	v_add_u32_dpp v78, v78, v78 row_bcast:31 row_mask:0xc bank_mask:0xf
	s_nop 1
	v_readlane_b32 s46, v78, 63
	s_cmpk_lt_u32 s46, 0x100
	s_cselect_b64 s[98:99], -1, 0
	s_cselect_b32 s8, 0, 0x00000010
	s_or_b32 s2, s2, s8
	v_cndmask_b32_e64 v247, v249, v79, s[98:99]
	v_cndmask_b32_e64 v248, v248, v77, s[98:99]
	s_cmpk_eq_u32 s46, 0x100
	s_cbranch_scc1 .Lmy_tk_done
	v_and_b32_e32 v249, v247, v213
	v_bcnt_u32_b32 v77, v249, v248
	v_xor_b32_e32 v79, v247, v249
	s_nop 0
	v_add_u32_dpp v78, v77, v77 row_shr:1 row_mask:0xf bank_mask:0xf bound_ctrl:0
	s_nop 1
	v_add_u32_dpp v78, v78, v78 row_shr:2 row_mask:0xf bank_mask:0xf
	s_nop 1
	v_add_u32_dpp v78, v78, v78 row_shr:4 row_mask:0xf bank_mask:0xf
	s_nop 1
	v_add_u32_dpp v78, v78, v78 row_shr:8 row_mask:0xf bank_mask:0xf
	s_nop 1
	v_add_u32_dpp v78, v78, v78 row_bcast:15 row_mask:0xa bank_mask:0xf
	s_nop 1
	v_add_u32_dpp v78, v78, v78 row_bcast:31 row_mask:0xc bank_mask:0xf
	s_nop 1
	v_readlane_b32 s46, v78, 63
	s_cmpk_lt_u32 s46, 0x100
	s_cselect_b64 s[98:99], -1, 0
	s_cselect_b32 s8, 0, 0x00000008
	s_or_b32 s2, s2, s8
	v_cndmask_b32_e64 v247, v249, v79, s[98:99]
	v_cndmask_b32_e64 v248, v248, v77, s[98:99]
	s_cmpk_eq_u32 s46, 0x100
	s_cbranch_scc1 .Lmy_tk_done
	v_and_b32_e32 v249, v247, v239
	v_bcnt_u32_b32 v77, v249, v248
	v_xor_b32_e32 v79, v247, v249
	s_nop 0
	v_add_u32_dpp v78, v77, v77 row_shr:1 row_mask:0xf bank_mask:0xf bound_ctrl:0
	s_nop 1
	v_add_u32_dpp v78, v78, v78 row_shr:2 row_mask:0xf bank_mask:0xf
	s_nop 1
	v_add_u32_dpp v78, v78, v78 row_shr:4 row_mask:0xf bank_mask:0xf
	s_nop 1
	v_add_u32_dpp v78, v78, v78 row_shr:8 row_mask:0xf bank_mask:0xf
	s_nop 1
	v_add_u32_dpp v78, v78, v78 row_bcast:15 row_mask:0xa bank_mask:0xf
	s_nop 1
	v_add_u32_dpp v78, v78, v78 row_bcast:31 row_mask:0xc bank_mask:0xf
	s_nop 1
	v_readlane_b32 s46, v78, 63
	s_cmpk_lt_u32 s46, 0x100
	s_cselect_b64 s[98:99], -1, 0
	s_cselect_b32 s8, 0, 0x00000004
	s_or_b32 s2, s2, s8
	v_cndmask_b32_e64 v247, v249, v79, s[98:99]
	v_cndmask_b32_e64 v248, v248, v77, s[98:99]
	s_cmpk_eq_u32 s46, 0x100
	s_cbranch_scc1 .Lmy_tk_done
	v_and_b32_e32 v249, v247, v235
	v_bcnt_u32_b32 v77, v249, v248
	v_xor_b32_e32 v79, v247, v249
	s_nop 0
	v_add_u32_dpp v78, v77, v77 row_shr:1 row_mask:0xf bank_mask:0xf bound_ctrl:0
	s_nop 1
	v_add_u32_dpp v78, v78, v78 row_shr:2 row_mask:0xf bank_mask:0xf
	s_nop 1
	v_add_u32_dpp v78, v78, v78 row_shr:4 row_mask:0xf bank_mask:0xf
	s_nop 1
	v_add_u32_dpp v78, v78, v78 row_shr:8 row_mask:0xf bank_mask:0xf
	s_nop 1
	v_add_u32_dpp v78, v78, v78 row_bcast:15 row_mask:0xa bank_mask:0xf
	s_nop 1
	v_add_u32_dpp v78, v78, v78 row_bcast:31 row_mask:0xc bank_mask:0xf
	s_nop 1
	v_readlane_b32 s46, v78, 63
	s_cmpk_lt_u32 s46, 0x100
	s_cselect_b64 s[98:99], -1, 0
	s_cselect_b32 s8, 0, 0x00000002
	s_or_b32 s2, s2, s8
	v_cndmask_b32_e64 v247, v249, v79, s[98:99]
	v_cndmask_b32_e64 v248, v248, v77, s[98:99]
	s_cmpk_eq_u32 s46, 0x100
	s_cbranch_scc1 .Lmy_tk_done
	v_and_b32_e32 v249, v247, v241
	v_bcnt_u32_b32 v77, v249, v248
	v_xor_b32_e32 v79, v247, v249
	s_nop 0
	v_add_u32_dpp v78, v77, v77 row_shr:1 row_mask:0xf bank_mask:0xf bound_ctrl:0
	s_nop 1
	v_add_u32_dpp v78, v78, v78 row_shr:2 row_mask:0xf bank_mask:0xf
	s_nop 1
	v_add_u32_dpp v78, v78, v78 row_shr:4 row_mask:0xf bank_mask:0xf
	s_nop 1
	v_add_u32_dpp v78, v78, v78 row_shr:8 row_mask:0xf bank_mask:0xf
	s_nop 1
	v_add_u32_dpp v78, v78, v78 row_bcast:15 row_mask:0xa bank_mask:0xf
	s_nop 1
	v_add_u32_dpp v78, v78, v78 row_bcast:31 row_mask:0xc bank_mask:0xf
	s_nop 1
	v_readlane_b32 s46, v78, 63
	s_cmpk_lt_u32 s46, 0x100
	s_cselect_b64 s[98:99], -1, 0
	s_cselect_b32 s8, 0, 0x00000001
	s_or_b32 s2, s2, s8
	v_cndmask_b32_e64 v247, v249, v79, s[98:99]
	v_cndmask_b32_e64 v248, v248, v77, s[98:99]
